# attention V-tile loads remapped to 1 KB-contiguous per wave load (same LDS image)
# speedup vs baseline: 1.0192x; 1.0134x over previous
; __device__ __forceinline__ void attn_load(const bf16_t* R1, const AttnItem& a, int tid, u32x4 (&kr)[8], u32x4 (&vr)[8]) {
;     const int lg = 2 * a.g;
;     ...
;     const bf16_t* Kq = (const bf16_t*)((const unsigned char*)R1 + R1_KA) + seq; const bf16_t* Vq = (const bf16_t*)((const unsigned char*)R1 + R1_VA) + seq;
;     const int row = tid >> 1, pv = tid & 1; const int jk = a.blk * 128 - 128 + row;
;     const u32x4 z = (u32x4){0u, 0u, 0u, 0u};
;     if (jk >= 0) { const bf16_t* src = Kq + (size_t)jk * 128; kr[0] = *(const u32x4*)(src + 8 * pv); kr[1] = *(const u32x4*)(src + 16 + 8 * pv); } else { kr[0] = z; kr[1] = z; }
; #pragma unroll
;     for (int i = 0; i < 6; ++i) {
;         const int task = tid + 512 * i; const int row2 = task / 12, v = 4 + task % 12; const int jk2 = a.blk * 128 - 128 + row2;
;         kr[2 + i] = (jk2 >= 0) ? *(const u32x4*)(Kq + (size_t)jk2 * 128 + v * 8) : z;
;     }
; #pragma unroll
;     for (int vi = 0; vi < 8; ++vi) vr[vi] = (jk >= 0) ? *(const u32x4*)(Vq + (size_t)jk * 128 + pv * 64 + vi * 8) : z;
.LBB0_580:
	s_or_b64 exec, exec, s[8:9]
	v_add_u32_e32 v24, s11, v137
	v_mov_b32_e32 v25, v20
	v_lshlrev_b64 v[24:25], 8, v[24:25]
	v_lshl_add_u64 v[24:25], s[6:7], 0, v[24:25]
	v_lshlrev_b32_e32 v26, 1, v138
	v_mov_b32_e32 v27, v20
	v_lshl_add_u64 v[40:41], v[24:25], 0, v[26:27]
	v_add_u32_e32 v24, s11, v139
	v_mov_b32_e32 v25, v20
	v_lshlrev_b64 v[24:25], 8, v[24:25]
	v_lshl_add_u64 v[24:25], s[6:7], 0, v[24:25]
	v_lshlrev_b32_e32 v26, 1, v140
	v_lshl_add_u64 v[42:43], v[24:25], 0, v[26:27]
	v_add_u32_e32 v24, s11, v141
	v_mov_b32_e32 v25, v20
	v_lshlrev_b64 v[24:25], 8, v[24:25]
	v_lshl_add_u64 v[24:25], s[6:7], 0, v[24:25]
	v_lshlrev_b32_e32 v26, 1, v142
	v_lshl_add_u64 v[44:45], v[24:25], 0, v[26:27]
	global_load_dwordx4 v[24:27], v[40:41], off offset:64
	global_load_dwordx4 v[28:31], v[42:43], off offset:64
	global_load_dwordx4 v[32:35], v[44:45], off offset:64
	v_readlane_b32 s0, v254, 55
	s_add_u32 s0, s0, s4
	v_readlane_b32 s1, v254, 57
	s_addc_u32 s1, s1, s5
	s_add_i32 s98, s11, 0xffffff80
	s_lshl_b32 s98, s98, 8
	s_ashr_i32 s99, s98, 31
	s_add_u32 s0, s0, s98
	s_addc_u32 s1, s1, s99
	v_lshlrev_b32_e32 v36, 4, v212
	s_cmp_eq_u32 s11, 0
	s_cbranch_scc1 .Lav_h_blk0
	global_load_dwordx4 v[20:23], v36, s[0:1]
	v_add_u32_e32 v36, 0x2000, v36
	global_load_dwordx4 v[40:43], v36, s[0:1]
	v_add_u32_e32 v36, 0x2000, v36
	global_load_dwordx4 v[48:51], v36, s[0:1]
	v_add_u32_e32 v36, 0x2000, v36
	global_load_dwordx4 v[44:47], v36, s[0:1]
	v_add_u32_e32 v36, 0x2000, v36
	s_branch .Lav_h_hi
.Lav_h_blk0:
	v_mov_b32_e32 v20, 0
	v_mov_b32_e32 v21, 0
	v_mov_b32_e32 v22, 0
	v_mov_b32_e32 v23, 0
	v_mov_b32_e32 v40, 0
	v_mov_b32_e32 v41, 0
	v_mov_b32_e32 v42, 0
	v_mov_b32_e32 v43, 0
	v_mov_b32_e32 v44, 0
	v_mov_b32_e32 v45, 0
	v_mov_b32_e32 v46, 0
	v_mov_b32_e32 v47, 0
	v_mov_b32_e32 v48, 0
	v_mov_b32_e32 v49, 0
	v_mov_b32_e32 v50, 0
	v_mov_b32_e32 v51, 0
	v_add_u32_e32 v36, 0x8000, v36
.Lav_h_hi:
	global_load_dwordx4 v[52:55], v36, s[0:1]
	v_add_u32_e32 v36, 0x2000, v36
	global_load_dwordx4 v[56:59], v36, s[0:1]
	v_add_u32_e32 v36, 0x2000, v36
	global_load_dwordx4 v[64:67], v36, s[0:1]
	v_add_u32_e32 v36, 0x2000, v36
	global_load_dwordx4 v[60:63], v36, s[0:1]
	s_andn2_b64 vcc, exec, s[2:3]
	s_cbranch_vccz .LBB0_590
	s_branch .LBB0_629

; __device__ __forceinline__ void attn_load(const bf16_t* R1, const AttnItem& a, int tid, u32x4 (&kr)[8], u32x4 (&vr)[8]) {
;     ...
;         const int task = tid + 512 * i; const int row2 = task / 12, v = 4 + task % 12; const int jk2 = a.blk * 128 - 128 + row2;
;         kr[2 + i] = (jk2 >= 0) ? *(const u32x4*)(Kq + (size_t)jk2 * 128 + v * 8) : z;
;     }
; #pragma unroll
;     for (int vi = 0; vi < 8; ++vi) vr[vi] = (jk >= 0) ? *(const u32x4*)(Vq + (size_t)jk * 128 + pv * 64 + vi * 8) : z;
; }
; __device__ __forceinline__ void p4_attn(const Params& p, LAS unsigned char* lds, const int dummy) {
;     const int tid = threadIdx.x, wid = __builtin_amdgcn_readfirstlane(tid >> 6), lane = tid & 63, r = lane & 15, q = lane >> 4;
;     unsigned char* ws = p.ws;
;     bf16_t* R1 = (bf16_t*)(ws + WS_R1);
;     const float* RC = (const float*)(ws + WS_ROPE); const float* RS = RC + 2048 * 16;
;     float* ML = (float*)((unsigned char*)p.out + OUT_ML);
;     LAS unsigned char* KA = lds + AT_KA; LAS unsigned char* VB = lds + AT_VB;
;     const float QSCALE = 0.08838834764831845f * 1.4426950408889634f;
;     u32x4 kr[8], vr[8];
;     int it = blockIdx.x;
;     if (it < 1536) { const AttnItem a0 = attn_item(it); attn_load(R1, a0, tid, kr, vr); }
;     for (; it < 1536; it += gridDim.x) {
;         const AttnItem a = attn_item(it);
;     ...
;         const int tokb = a.b * SEQ; const int qcol = g * 512 + hh * 128;
;         {
;             const int row = tid >> 1, pv = tid & 1; const int jk = blk * 128 - 128 + row;
;             u32x4 o1 = kr[0], o2 = kr[1];
;             if (jk >= 0) {
;                 const int pos = jk * dil + rr;
;                 float x1[8], x2[8]; unpack8(kr[0], x1); unpack8(kr[1], x2);
;                 const float4 ca = *(const float4*)(RC + pos * 16 + 8 * pv), cb = *(const float4*)(RC + pos * 16 + 8 * pv + 4);
;                 const float4 sa = *(const float4*)(RS + pos * 16 + 8 * pv), sb = *(const float4*)(RS + pos * 16 + 8 * pv + 4);
;                 const float cc[8] = {ca.x, ca.y, ca.z, ca.w, cb.x, cb.y, cb.z, cb.w}, sn[8] = {sa.x, sa.y, sa.z, sa.w, sb.x, sb.y, sb.z, sb.w};
;                 float y1[8], y2[8];
; #pragma unroll
;                 for (int e = 0; e < 8; ++e) { y1[e] = x1[e] * cc[e] - x2[e] * sn[e]; y2[e] = x2[e] * cc[e] + x1[e] * sn[e]; }
;                 o1 = pack8(y1); o2 = pack8(y2);
;             }
.LBB0_590:
	s_add_u32 s2, s88, 0xff80000
	s_addc_u32 s3, s89, 0
	s_add_u32 s4, s88, 0xffa0000
	v_mov_b32_e32 v36, 0
	v_lshlrev_b32_e32 v70, 1, v212
	s_addc_u32 s5, s89, 0
	v_lshlrev_b32_e32 v68, 2, v130
	v_mov_b32_e32 v69, v36
	v_and_b32_e32 v70, 32, v70
	v_mov_b32_e32 v71, v36
	v_lshl_add_u64 v[114:115], s[4:5], 0, v[68:69]
	v_lshl_add_u64 v[118:119], s[4:5], 0, v[70:71]
	s_mov_b32 s4, 0x15555556
	v_add_u32_e32 v78, 0x200, v212
	v_mul_hi_u32 v79, v78, s4
	v_mul_u32_u24_e32 v80, 12, v79
	v_sub_u32_e32 v78, v78, v80
	v_or_b32_e32 v80, 0x400, v212
	v_mul_hi_u32 v81, v80, s4
	v_mul_u32_u24_e32 v82, 12, v81
	v_sub_u32_e32 v80, v80, v82
	v_add_u32_e32 v82, 0x600, v212
	v_mul_hi_u32 v83, v82, s4
	v_mul_u32_u24_e32 v84, 12, v83
	v_mbcnt_lo_u32_b32 v90, -1, 0
	v_writelane_b32 v254, s82, 51
	v_sub_u32_e32 v82, v82, v84
	v_or_b32_e32 v84, 0x800, v212
	v_mbcnt_hi_u32_b32 v90, -1, v90
	v_writelane_b32 v254, s83, 52
	v_mul_hi_u32 v85, v84, s4
	v_and_b32_e32 v92, 64, v90
	v_writelane_b32 v254, s68, 29
	s_add_i32 s1, 0, 0x11000
	v_mul_u32_u24_e32 v86, 12, v85
	v_xor_b32_e32 v91, 16, v90
	v_add_u32_e32 v92, 64, v92
	v_writelane_b32 v254, s69, 30
	v_bfe_u32 v39, v212, 4, 2
	v_lshl_add_u64 v[112:113], s[2:3], 0, v[68:69]
	s_movk_i32 s6, 0x110
	s_movk_i32 s0, 0x120
	v_mov_b32_e32 v68, s1
	v_sub_u32_e32 v84, v84, v86
	v_add_u32_e32 v86, 0xa00, v212
	v_cmp_lt_i32_e32 vcc, v91, v92
	v_writelane_b32 v254, s70, 31
	v_mad_u32_u24 v69, v38, s6, 0
	v_mad_u32_u24 v73, v38, s0, v68
	v_lshlrev_b32_e32 v68, 3, v39
	v_lshl_add_u64 v[116:117], s[2:3], 0, v[70:71]
	v_cmp_gt_u32_e64 s[2:3], 2, v39
	v_add_u32_e32 v144, 0xffffff80, v38
	v_lshl_add_u32 v70, v39, 4, 0
	v_lshlrev_b32_e32 v38, 2, v39
	v_cmp_eq_u32_e64 s[16:17], 0, v39
	v_mul_hi_u32 v39, v212, s4
	v_mul_hi_u32 v87, v86, s4
	s_lshr_b32 s4, s10, 6
	v_cndmask_b32_e32 v91, v90, v91, vcc
	v_writelane_b32 v254, s71, 32
	v_and_b32_e32 v37, 15, v212
	s_lshl_b32 s5, s4, 4
	v_lshlrev_b32_e32 v146, 2, v91
	v_xor_b32_e32 v91, 32, v90
	v_writelane_b32 v254, s72, 33
	v_or_b32_e32 v145, s5, v37
	s_sub_i32 s18, 8, s4
	v_cmp_lt_i32_e32 vcc, v91, v92
	s_add_i32 s4, s5, 16
	s_add_i32 s7, s5, 32
	s_add_i32 s8, s5, 48
	s_add_i32 s9, s5, 64
	s_add_i32 s10, s5, 0x50
	s_add_i32 s11, s5, 0x60
	s_add_i32 s12, s5, 0x70
	s_add_i32 s13, s5, 0x80
	v_writelane_b32 v254, s73, 34
	v_add_u32_e32 v89, 0x80, v145
	v_cndmask_b32_e32 v90, v90, v91, vcc
	v_or_b32_e32 v91, s4, v37
	v_or_b32_e32 v92, s7, v37
	v_or_b32_e32 v93, s8, v37
	v_or_b32_e32 v94, s9, v37
	v_or_b32_e32 v95, s10, v37
	v_or_b32_e32 v96, s11, v37
	v_or_b32_e32 v97, s12, v37
	v_or_b32_e32 v37, s13, v37
	v_or_b32_e32 v148, s5, v38
	v_writelane_b32 v254, s74, 35
	v_mul_u32_u24_e32 v77, 12, v39
	v_mad_u32_u24 v39, v39, s6, 0
	v_mad_u32_u24 v79, v79, s6, 0
	v_mad_u32_u24 v81, v81, s6, 0
	v_mad_u32_u24 v83, v83, s6, 0
	v_mad_u32_u24 v85, v85, s6, 0
	v_mul_u32_u24_e32 v88, 12, v87
	v_mad_u32_u24 v87, v87, s6, 0
	v_lshlrev_b32_e32 v147, 2, v90
	v_mul_lo_u32 v90, v145, s6
	v_mul_lo_u32 v91, v91, s6
	v_mul_lo_u32 v92, v92, s6
	v_mul_lo_u32 v93, v93, s6
	v_mul_lo_u32 v94, v94, s6
	v_mul_lo_u32 v95, v95, s6
	v_mul_lo_u32 v96, v96, s6
	v_mul_lo_u32 v97, v97, s6
	v_mul_lo_u32 v37, v37, s6
	v_sub_u32_e32 v98, v89, v148
	s_movk_i32 s6, 0x81
	v_writelane_b32 v254, s75, 36
	v_cmp_gt_u32_e64 s[20:21], s6, v98
	v_sub_u32_e32 v98, v148, v89
	s_movk_i32 s33, 0xff7e
	v_writelane_b32 v254, s20, 61
	v_or_b32_e32 v149, 2, v148
	v_or_b32_e32 v150, 3, v148
	v_writelane_b32 v254, s21, 62
	v_cmp_lt_u32_e64 s[20:21], s33, v98
	v_sub_u32_e32 v98, v89, v149
	v_or_b32_e32 v151, s4, v38
	v_writelane_b32 v254, s20, 43
	v_or_b32_e32 v152, 2, v151
	v_or_b32_e32 v153, 3, v151
	v_writelane_b32 v254, s21, 44
	v_cmp_gt_u32_e64 s[20:21], s6, v98
	v_sub_u32_e32 v98, v89, v150
	v_or_b32_e32 v154, s7, v38
	v_writelane_b32 v254, s20, 37
	v_or_b32_e32 v155, 2, v154
	v_or_b32_e32 v156, 3, v154
	v_writelane_b32 v254, s21, 38
	v_cmp_gt_u32_e64 s[20:21], s6, v98
	v_sub_u32_e32 v98, v89, v151
	v_or_b32_e32 v157, s8, v38
	v_writelane_b32 v254, s20, 39
	v_or_b32_e32 v158, 2, v157
	v_or_b32_e32 v159, 3, v157
	v_writelane_b32 v254, s21, 40
	v_cmp_gt_u32_e64 s[20:21], s6, v98
	v_sub_u32_e32 v98, v151, v89
	v_or_b32_e32 v160, s9, v38
	v_writelane_b32 v254, s20, 41
	v_or_b32_e32 v161, 2, v160
	v_or_b32_e32 v162, 3, v160
	v_writelane_b32 v254, s21, 42
	v_cmp_lt_u32_e64 s[20:21], s33, v98
	v_sub_u32_e32 v98, v89, v152
	v_or_b32_e32 v163, s10, v38
	v_writelane_b32 v254, s20, 47
	v_or_b32_e32 v164, 2, v163
	v_or_b32_e32 v165, 3, v163
	v_writelane_b32 v254, s21, 48
	v_cmp_gt_u32_e64 s[20:21], s6, v98
	v_sub_u32_e32 v98, v89, v153
; #define LAS __attribute__((address_space(3)))
; __device__ __forceinline__ void p4_attn(const Params& p, LAS unsigned char* lds, const int dummy) {
;     ...
;             *(LAS u32x4*)(KA + row * KA_STRIDE + (8 * pv) * 2) = o1;
;             *(LAS u32x4*)(KA + row * KA_STRIDE + (16 + 8 * pv) * 2) = o2;
; #pragma unroll
;             for (int i = 0; i < 6; ++i) { const int task = tid + 512 * i; const int row2 = task / 12, v = 4 + task % 12; *(LAS u32x4*)(KA + row2 * KA_STRIDE + v * 16) = kr[2 + i]; }
; #pragma unroll
;             for (int vi = 0; vi < 8; ++vi) *(LAS u32x4*)(VB + row * VB_STRIDE + (pv * 64 + vi * 8) * 2) = vr[vi];
;     ...
;         float mx = -1e30f;
; #pragma unroll
;         for (int i = 0; i < 9; ++i)
; #pragma unroll
;             for (int j = 0; j < 4; ++j) {
;                 const int kl = 16 * (wid + i) + 4 * q + j; const int dist = ql - kl + 128; const int jk = blk * 128 - 128 + kl;
;                 const bool valid = (dist >= 0) && (dist <= 128) && (jk >= 0);
;                 sT[i][j] = valid ? sT[i][j] : -1e30f; mx = fmaxf(mx, sT[i][j]);
	v_or_b32_e32 v166, s11, v38
	v_writelane_b32 v254, s20, 49
	v_or_b32_e32 v167, 2, v166
	v_or_b32_e32 v168, 3, v166
	v_writelane_b32 v254, s21, 50
	v_cmp_gt_u32_e64 s[20:21], s6, v98
	v_sub_u32_e32 v98, v89, v154
	v_cmp_gt_u32_e64 s[22:23], s6, v98
	v_sub_u32_e32 v98, v154, v89
	v_cmp_lt_u32_e64 s[24:25], s33, v98
	v_sub_u32_e32 v98, v89, v155
	v_cmp_gt_u32_e64 s[26:27], s6, v98
	v_sub_u32_e32 v98, v89, v156
	v_cmp_gt_u32_e64 s[28:29], s6, v98
	v_sub_u32_e32 v98, v89, v157
	v_cmp_gt_u32_e64 s[30:31], s6, v98
	v_sub_u32_e32 v98, v157, v89
	v_cmp_lt_u32_e64 s[34:35], s33, v98
	v_sub_u32_e32 v98, v89, v158
	v_cmp_gt_u32_e64 s[36:37], s6, v98
	v_sub_u32_e32 v98, v89, v159
	v_cmp_gt_u32_e64 s[38:39], s6, v98
	v_sub_u32_e32 v98, v89, v160
	v_cmp_gt_u32_e64 s[40:41], s6, v98
	v_sub_u32_e32 v98, v160, v89
	v_cmp_lt_u32_e64 s[42:43], s33, v98
	v_sub_u32_e32 v98, v89, v161
	v_cmp_gt_u32_e64 s[44:45], s6, v98
	v_sub_u32_e32 v98, v89, v162
	v_cmp_gt_u32_e64 s[46:47], s6, v98
	v_sub_u32_e32 v98, v89, v163
	v_cmp_gt_u32_e64 s[48:49], s6, v98
	v_sub_u32_e32 v98, v163, v89
	v_cmp_lt_u32_e64 s[50:51], s33, v98
	v_sub_u32_e32 v98, v89, v164
	v_cmp_gt_u32_e64 s[52:53], s6, v98
	v_sub_u32_e32 v98, v89, v165
	v_cmp_gt_u32_e64 s[54:55], s6, v98
	v_sub_u32_e32 v98, v89, v166
	v_cmp_gt_u32_e64 s[56:57], s6, v98
	v_sub_u32_e32 v98, v166, v89
	v_cmp_lt_u32_e64 s[58:59], s33, v98
	v_sub_u32_e32 v98, v89, v167
	v_cmp_gt_u32_e64 s[60:61], s6, v98
	v_sub_u32_e32 v98, v89, v168
	v_or_b32_e32 v169, s12, v38
	v_cmp_gt_u32_e64 s[62:63], s6, v98
	v_sub_u32_e32 v98, v89, v169
	v_cmp_gt_u32_e64 s[64:65], s6, v98
	v_sub_u32_e32 v98, v169, v89
	v_or_b32_e32 v170, 2, v169
	v_cmp_lt_u32_e64 s[66:67], s33, v98
	v_sub_u32_e32 v98, v89, v170
	v_or_b32_e32 v171, 3, v169
	v_cmp_gt_u32_e64 s[68:69], s6, v98
	v_sub_u32_e32 v98, v89, v171
	v_cmp_gt_u32_e64 s[70:71], s6, v98
	v_or_b32_e32 v98, s13, v38
	v_sub_u32_e32 v99, v89, v98
	v_sub_u32_e32 v89, v98, v89
	v_bfe_u32 v71, v212, 2, 2
	v_cmp_lt_u32_e64 s[74:75], s33, v89
	v_sub_u32_e32 v89, v145, v98
	v_or3_b32 v76, v71, v38, 16
	v_cmp_gt_u32_e64 s[72:73], s6, v99
	v_add_u32_e32 v99, 0x7e, v89
	v_add_u32_e32 v89, 0x7d, v89
	v_lshlrev_b32_e32 v75, 3, v212
	v_cmp_gt_u32_e64 s[76:77], s6, v99
	v_cmp_gt_u32_e64 s[78:79], s6, v89
	v_or_b32_e32 v89, v148, v71
	v_add_u32_e32 v99, s5, v76
	v_or_b32_e32 v100, v154, v71
	v_add_u32_e32 v101, s7, v76
	v_or_b32_e32 v102, v160, v71
	v_add_u32_e32 v103, s9, v76
	v_or_b32_e32 v104, v166, v71
	v_add_u32_e32 v76, s11, v76
	v_and_b32_e32 v75, 24, v75
	v_sub_u32_e32 v77, v212, v77
	v_sub_u32_e32 v86, v86, v88
	v_mul_lo_u32 v89, v89, s0
	v_mul_lo_u32 v99, v99, s0
	v_mul_lo_u32 v100, v100, s0
	v_mul_lo_u32 v101, v101, s0
	v_mul_lo_u32 v102, v102, s0
	v_mul_lo_u32 v103, v103, s0
	v_mul_lo_u32 v104, v104, s0
	v_mul_lo_u32 v76, v76, s0
	v_or_b32_e32 v71, v98, v71
	v_lshlrev_b32_e32 v72, 4, v190
	v_lshlrev_b32_e32 v74, 7, v190
	v_lshlrev_b32_e32 v77, 4, v77
	v_lshlrev_b32_e32 v78, 4, v78
	v_lshlrev_b32_e32 v80, 4, v80
	v_lshlrev_b32_e32 v82, 4, v82
	v_lshlrev_b32_e32 v84, 4, v84
	v_lshlrev_b32_e32 v86, 4, v86
	v_add_u32_e32 v88, s1, v75
	v_add_u32_e32 v89, s1, v89
	v_add_u32_e32 v99, s1, v99
	v_add_u32_e32 v100, s1, v100
	v_add_u32_e32 v101, s1, v101
	v_add_u32_e32 v102, s1, v102
	v_add_u32_e32 v103, s1, v103
	v_add_u32_e32 v104, s1, v104
	v_add_u32_e32 v76, s1, v76
	v_mul_lo_u32 v71, v71, s0
	v_add_u32_e32 v172, v69, v72
	v_add_u32_e32 v173, v39, v77
	v_add_u32_e32 v174, v79, v78
	v_add_u32_e32 v175, v81, v80
	v_add_u32_e32 v176, v83, v82
	v_add_u32_e32 v177, v85, v84
	v_add_u32_e32 v178, v87, v86
	v_and_b32_e32 v179, 0x1f0, v212
	v_lshlrev_b32_e32 v179, 1, v179
	v_lshl_add_u32 v179, v212, 4, v179
	v_add_u32_e32 v179, 0x11000, v179
	v_lshlrev_b32_e32 v120, 1, v68
	s_mov_b32 s8, s84
	s_mov_b32 s84, 0x3e0293ee
	v_add_u32_e32 v180, v70, v90
	v_add_u32_e32 v181, v70, v91
	v_add_u32_e32 v182, v70, v92
	v_add_u32_e32 v183, v70, v93
	v_add_u32_e32 v184, v70, v94
	v_add_u32_e32 v185, v70, v95
	v_add_u32_e32 v186, v70, v96
	v_add_u32_e32 v187, v70, v97
	v_add_u32_e32 v188, v70, v37
	s_mov_b32 s85, 0xefa18f08
	s_mov_b32 s33, 0xc2fc0000
	v_add_u32_e32 v189, v89, v75
	v_add_u32_e32 v190, v99, v75
	v_add_u32_e32 v191, v100, v75
	v_add_u32_e32 v192, v101, v75
	v_add_u32_e32 v193, v102, v75
	v_add_u32_e32 v194, v103, v75
	v_add_u32_e32 v195, v104, v75
	v_add_u32_e32 v196, v76, v75
	v_add_u32_e32 v197, v88, v71
	v_lshlrev_b32_e32 v122, 1, v38
	v_mov_b32_e32 v198, 0xf149f2ca
	v_mov_b32_e32 v199, 0x42800000
	v_not_b32_e32 v200, 63
	s_mov_b32 s80, 0
	v_writelane_b32 v254, s8, 54
	s_branch .LBB0_592

; #define LAS __attribute__((address_space(3)))
; __device__ __forceinline__ void p4_attn(const Params& p, LAS unsigned char* lds, const int dummy) {
;     ...
;             *(LAS u32x4*)(KA + row * KA_STRIDE + (8 * pv) * 2) = o1;
;             *(LAS u32x4*)(KA + row * KA_STRIDE + (16 + 8 * pv) * 2) = o2;
; #pragma unroll
;             for (int i = 0; i < 6; ++i) { const int task = tid + 512 * i; const int row2 = task / 12, v = 4 + task % 12; *(LAS u32x4*)(KA + row2 * KA_STRIDE + v * 16) = kr[2 + i]; }
; #pragma unroll
;             for (int vi = 0; vi < 8; ++vi) *(LAS u32x4*)(VB + row * VB_STRIDE + (pv * 64 + vi * 8) * 2) = vr[vi];
;         }
;         const int ql = 16 * wid + r; const int jq = blk * 128 + ql; const int posq = jq * dil + rr; const size_t tq = (size_t)(tokb + posq);
;         bf16x8 qf[4];
;         {
;             bf16_t* qsrc = R1 + tq * QZ_LD + qcol;
; #pragma unroll
;             for (int kk = 0; kk < 4; ++kk) {
;                 const u32x4 av = *(const u32x4*)(qsrc + 32 * kk + 8 * q);
;                 float x[8]; unpack8(av, x);
;                 if (kk == 0) {
;                     const int fi = 8 * (q & 1);
;                     const float4 ca = *(const float4*)(RC + posq * 16 + fi), cb = *(const float4*)(RC + posq * 16 + fi + 4);
;                     const float4 sa = *(const float4*)(RS + posq * 16 + fi), sb = *(const float4*)(RS + posq * 16 + fi + 4);
;                     const float cc[8] = {ca.x, ca.y, ca.z, ca.w, cb.x, cb.y, cb.z, cb.w}, sn[8] = {sa.x, sa.y, sa.z, sa.w, sb.x, sb.y, sb.z, sb.w};
; #pragma unroll
;                     for (int e = 0; e < 8; ++e) { const float xo = __shfl_xor(x[e], 32); x[e] = (q < 2) ? (x[e] * cc[e] - xo * sn[e]) : (x[e] * cc[e] + xo * sn[e]); }
;                 }
; #pragma unroll
;                 for (int e = 0; e < 8; ++e) x[e] *= QSCALE;
;                 qf[kk] = __builtin_bit_cast(bf16x8, pack8(x));
;             }
;         }
;         __syncthreads();
.LBB0_594:
	s_or_b64 exec, exec, s[0:1]
	s_mul_hi_i32 s0, s8, 0x2aaaaaab
	v_add_u32_e32 v37, s11, v145
	s_lshr_b32 s1, s0, 31
	s_lshr_b32 s0, s0, 5
	v_lshlrev_b32_e32 v37, s4, v37
	s_add_i32 s1, s0, s1
	v_add_u32_e32 v37, s5, v37
	s_bfe_u32 s10, s8, 0x20004
	v_lshl_add_u32 v124, s1, 11, v37
	s_lshl_b32 s0, s9, 9
	s_lshl_b32 s6, s10, 7
	v_ashrrev_i32_e32 v125, 31, v124
	v_readlane_b32 s4, v254, 20
	s_or_b32 s0, s0, s6
	v_lshlrev_b64 v[38:39], 12, v[124:125]
	v_readlane_b32 s5, v254, 21
	s_ashr_i32 s1, s0, 31
	v_mov_b32_e32 v121, v36
	v_lshl_add_u64 v[38:39], s[4:5], 0, v[38:39]
	v_lshl_add_u64 v[126:127], s[0:1], 1, v[38:39]
	v_lshlrev_b32_e32 v68, 4, v37
	v_mov_b32_e32 v69, v36
	v_lshl_add_u64 v[38:39], v[126:127], 0, v[120:121]
	v_lshlrev_b64 v[68:69], 2, v[68:69]
	global_load_dwordx4 v[108:111], v[38:39], off
	v_lshl_add_u64 v[70:71], v[118:119], 0, v[68:69]
	v_lshl_add_u64 v[68:69], v[116:117], 0, v[68:69]
	global_load_dwordx4 v[80:83], v[68:69], off offset:16
	global_load_dwordx4 v[88:91], v[68:69], off
	global_load_dwordx4 v[84:87], v[70:71], off offset:16
	global_load_dwordx4 v[92:95], v[70:71], off
	global_load_dwordx4 v[76:79], v[38:39], off offset:64
	global_load_dwordx4 v[72:75], v[38:39], off offset:128
	s_nop 0
	global_load_dwordx4 v[68:71], v[38:39], off offset:192
	ds_write_b128 v172, v[96:99]
	ds_write_b128 v172, v[100:103] offset:32
	ds_write_b128 v173, v[8:11] offset:64
	ds_write_b128 v174, v[12:15] offset:64
	ds_write_b128 v175, v[16:19] offset:64
	ds_write_b128 v176, v[24:27] offset:64
	ds_write_b128 v177, v[28:31] offset:64
	ds_write_b128 v178, v[32:35] offset:64
	ds_write_b128 v179, v[20:23]
	ds_write_b128 v179, v[40:43] offset:9216
	ds_write_b128 v179, v[48:51] offset:18432
	ds_write_b128 v179, v[44:47] offset:27648
	ds_write_b128 v179, v[52:55] offset:36864
	ds_write_b128 v179, v[56:59] offset:46080
	ds_write_b128 v179, v[64:67] offset:55296
	ds_write_b128 v179, v[60:63] offset:64512
	v_readlane_b32 s0, v254, 51
	s_add_i32 s8, s8, s0
	s_cmpk_gt_i32 s8, 0x5ff
	s_cselect_b64 s[86:87], -1, 0
	s_and_b64 vcc, exec, s[86:87]
	v_readlane_b32 s1, v254, 52
	s_waitcnt lgkmcnt(0)
	s_barrier
	s_waitcnt vmcnt(7)
	v_lshlrev_b32_e32 v106, 16, v108
	v_and_b32_e32 v107, 0xffff0000, v108
	v_lshlrev_b32_e32 v102, 16, v109
	v_and_b32_e32 v103, 0xffff0000, v109
	v_lshlrev_b32_e32 v98, 16, v110
	v_and_b32_e32 v99, 0xffff0000, v110
	v_lshlrev_b32_e32 v96, 16, v111
	v_and_b32_e32 v97, 0xffff0000, v111
	ds_bpermute_b32 v110, v147, v106
	ds_bpermute_b32 v111, v147, v107
	ds_bpermute_b32 v108, v147, v102
	ds_bpermute_b32 v109, v147, v103
	ds_bpermute_b32 v104, v147, v98
	ds_bpermute_b32 v105, v147, v99
	ds_bpermute_b32 v100, v147, v96
	ds_bpermute_b32 v101, v147, v97

; __device__ __forceinline__ void attn_load(const bf16_t* R1, const AttnItem& a, int tid, u32x4 (&kr)[8], u32x4 (&vr)[8]) {
;     const int lg = 2 * a.g;
;     ...
;     const bf16_t* Kq = (const bf16_t*)((const unsigned char*)R1 + R1_KA) + seq; const bf16_t* Vq = (const bf16_t*)((const unsigned char*)R1 + R1_VA) + seq;
;     const int row = tid >> 1, pv = tid & 1; const int jk = a.blk * 128 - 128 + row;
;     const u32x4 z = (u32x4){0u, 0u, 0u, 0u};
;     if (jk >= 0) { const bf16_t* src = Kq + (size_t)jk * 128; kr[0] = *(const u32x4*)(src + 8 * pv); kr[1] = *(const u32x4*)(src + 16 + 8 * pv); } else { kr[0] = z; kr[1] = z; }
; #pragma unroll
;     for (int i = 0; i < 6; ++i) {
;         const int task = tid + 512 * i; const int row2 = task / 12, v = 4 + task % 12; const int jk2 = a.blk * 128 - 128 + row2;
;         kr[2 + i] = (jk2 >= 0) ? *(const u32x4*)(Kq + (size_t)jk2 * 128 + v * 8) : z;
;     }
; #pragma unroll
;     for (int vi = 0; vi < 8; ++vi) vr[vi] = (jk >= 0) ? *(const u32x4*)(Vq + (size_t)jk * 128 + pv * 64 + vi * 8) : z;
.LBB0_603:
	s_or_b64 exec, exec, s[6:7]
	v_add_u32_e32 v22, s12, v137
	v_mov_b32_e32 v23, v36
	v_lshlrev_b64 v[22:23], 8, v[22:23]
	v_lshl_add_u64 v[22:23], s[82:83], 0, v[22:23]
	v_lshlrev_b32_e32 v24, 1, v138
	v_mov_b32_e32 v25, v36
	v_lshl_add_u64 v[22:23], v[22:23], 0, v[24:25]
	v_add_u32_e32 v24, s12, v139
	v_lshlrev_b64 v[24:25], 8, v[24:25]
	v_lshl_add_u64 v[24:25], s[82:83], 0, v[24:25]
	v_lshlrev_b32_e32 v26, 1, v140
	v_mov_b32_e32 v27, v36
	v_lshl_add_u64 v[28:29], v[24:25], 0, v[26:27]
	global_load_dwordx4 v[24:27], v[22:23], off offset:64
	s_nop 0
	global_load_dwordx4 v[28:31], v[28:29], off offset:64
	v_add_u32_e32 v22, s12, v141
	v_mov_b32_e32 v23, v36
	v_lshlrev_b64 v[22:23], 8, v[22:23]
	v_lshl_add_u64 v[22:23], s[82:83], 0, v[22:23]
	v_lshlrev_b32_e32 v32, 1, v142
	v_mov_b32_e32 v33, v36
	v_lshl_add_u64 v[22:23], v[22:23], 0, v[32:33]
	global_load_dwordx4 v[32:35], v[22:23], off offset:64
	v_readlane_b32 s0, v254, 55
	s_add_u32 s0, s0, s4
	v_readlane_b32 s1, v254, 57
	s_addc_u32 s1, s1, s5
	s_add_i32 s98, s12, 0xffffff80
	s_lshl_b32 s98, s98, 8
	s_ashr_i32 s99, s98, 31
	s_add_u32 s0, s0, s98
	s_addc_u32 s1, s1, s99
	v_lshlrev_b32_e32 v128, 4, v212
	s_cmp_eq_u32 s12, 0
	s_cbranch_scc1 .Lav_l_blk0
	global_load_dwordx4 v[20:23], v128, s[0:1]
	v_add_u32_e32 v128, 0x2000, v128
	global_load_dwordx4 v[40:43], v128, s[0:1]
	v_add_u32_e32 v128, 0x2000, v128
	global_load_dwordx4 v[48:51], v128, s[0:1]
	v_add_u32_e32 v128, 0x2000, v128
	global_load_dwordx4 v[44:47], v128, s[0:1]
	v_add_u32_e32 v128, 0x2000, v128
	s_branch .Lav_l_hi
.Lav_l_blk0:
	v_mov_b32_e32 v20, 0
	v_mov_b32_e32 v21, 0
	v_mov_b32_e32 v22, 0
	v_mov_b32_e32 v23, 0
	v_mov_b32_e32 v40, 0
	v_mov_b32_e32 v41, 0
	v_mov_b32_e32 v42, 0
	v_mov_b32_e32 v43, 0
	v_mov_b32_e32 v44, 0
	v_mov_b32_e32 v45, 0
	v_mov_b32_e32 v46, 0
	v_mov_b32_e32 v47, 0
	v_mov_b32_e32 v48, 0
	v_mov_b32_e32 v49, 0
	v_mov_b32_e32 v50, 0
	v_mov_b32_e32 v51, 0
	v_add_u32_e32 v128, 0x8000, v128
.Lav_l_hi:
	global_load_dwordx4 v[52:55], v128, s[0:1]
	v_add_u32_e32 v128, 0x2000, v128
	global_load_dwordx4 v[56:59], v128, s[0:1]
	v_add_u32_e32 v128, 0x2000, v128
	global_load_dwordx4 v[64:67], v128, s[0:1]
	v_add_u32_e32 v128, 0x2000, v128
	global_load_dwordx4 v[60:63], v128, s[0:1]
